# attention key-rope loads hoisted above K/V wait; mLSTM prologue running-max recurrence made straight-line (register chain, wide LDS ops)
# speedup vs baseline: 1.0043x; 1.0018x over previous
; #define LAS __attribute__((address_space(3)))
; __device__ __forceinline__ void p2_mlstm(const Params& p, LAS unsigned char* lds) {
;     ...
;         __syncthreads();
;         if (tid < 128) ((LAS unsigned*)NV)[tid] = 0u;
;         if (tid == 0) {
;             float mprev = 0.f;
; #pragma unroll 1
;             for (int c = 0; c < 16; ++c) { const float mm = fmaxf(mprev, PCT[c]); MPREV[c] = mprev; MM127[c] = mm; mprev = PBT[c] + mm; }
;         }
.LBB0_243:
	v_readlane_b32 s6, v254, 49
	v_readlane_b32 s7, v254, 50
	s_waitcnt lgkmcnt(0)
	s_barrier
	s_and_saveexec_b64 s[34:35], s[6:7]
	ds_write_b32 v192, v4
	s_or_b64 exec, exec, s[34:35]
	v_readlane_b32 s6, v254, 1
	v_readlane_b32 s7, v254, 2
	s_and_saveexec_b64 s[34:35], s[6:7]
	s_cbranch_execz .LBB0_248
	v_mov_b32_e32 v6, 0x24800
	ds_read_b128 v[100:103], v6 offset:64
	ds_read_b128 v[104:107], v6 offset:80
	ds_read_b128 v[108:111], v6 offset:96
	ds_read_b128 v[112:115], v6 offset:112
	ds_read_b128 v[116:119], v6
	ds_read_b128 v[120:123], v6 offset:16
	ds_read_b128 v[124:127], v6 offset:32
	ds_read_b128 v[128:131], v6 offset:48
	v_mov_b32_e32 v5, 0
	s_waitcnt lgkmcnt(0)
	v_mov_b32_e32 v132, v5
	v_max_f32_e32 v7, v5, v5
	v_max_f32_e32 v16, v100, v100
	v_max_f32_e32 v16, v7, v16
	v_add_f32_e32 v5, v16, v116
	v_mov_b32_e32 v133, v5
	v_max_f32_e32 v7, v5, v5
	v_max_f32_e32 v17, v101, v101
	v_max_f32_e32 v17, v7, v17
	v_add_f32_e32 v5, v17, v117
	v_mov_b32_e32 v134, v5
	v_max_f32_e32 v7, v5, v5
	v_max_f32_e32 v18, v102, v102
	v_max_f32_e32 v18, v7, v18
	v_add_f32_e32 v5, v18, v118
	v_mov_b32_e32 v135, v5
	v_max_f32_e32 v7, v5, v5
	v_max_f32_e32 v19, v103, v103
	v_max_f32_e32 v19, v7, v19
	v_add_f32_e32 v5, v19, v119
	v_mov_b32_e32 v136, v5
	v_max_f32_e32 v7, v5, v5
	v_max_f32_e32 v20, v104, v104
	v_max_f32_e32 v20, v7, v20
	v_add_f32_e32 v5, v20, v120
	v_mov_b32_e32 v137, v5
	v_max_f32_e32 v7, v5, v5
	v_max_f32_e32 v21, v105, v105
	v_max_f32_e32 v21, v7, v21
	v_add_f32_e32 v5, v21, v121
	v_mov_b32_e32 v138, v5
	v_max_f32_e32 v7, v5, v5
	v_max_f32_e32 v22, v106, v106
	v_max_f32_e32 v22, v7, v22
	v_add_f32_e32 v5, v22, v122
	v_mov_b32_e32 v139, v5
	v_max_f32_e32 v7, v5, v5
	v_max_f32_e32 v23, v107, v107
	v_max_f32_e32 v23, v7, v23
	v_add_f32_e32 v5, v23, v123
	v_mov_b32_e32 v140, v5
	v_max_f32_e32 v7, v5, v5
	v_max_f32_e32 v24, v108, v108
	v_max_f32_e32 v24, v7, v24
	v_add_f32_e32 v5, v24, v124
	v_mov_b32_e32 v141, v5
	v_max_f32_e32 v7, v5, v5
	v_max_f32_e32 v25, v109, v109
	v_max_f32_e32 v25, v7, v25
	v_add_f32_e32 v5, v25, v125
	v_mov_b32_e32 v142, v5
	v_max_f32_e32 v7, v5, v5
	v_max_f32_e32 v26, v110, v110
	v_max_f32_e32 v26, v7, v26
	v_add_f32_e32 v5, v26, v126
	v_mov_b32_e32 v143, v5
	v_max_f32_e32 v7, v5, v5
	v_max_f32_e32 v27, v111, v111
	v_max_f32_e32 v27, v7, v27
	v_add_f32_e32 v5, v27, v127
	v_mov_b32_e32 v144, v5
	v_max_f32_e32 v7, v5, v5
	v_max_f32_e32 v28, v112, v112
	v_max_f32_e32 v28, v7, v28
	v_add_f32_e32 v5, v28, v128
	v_mov_b32_e32 v145, v5
	v_max_f32_e32 v7, v5, v5
	v_max_f32_e32 v29, v113, v113
	v_max_f32_e32 v29, v7, v29
	v_add_f32_e32 v5, v29, v129
	v_mov_b32_e32 v146, v5
	v_max_f32_e32 v7, v5, v5
	v_max_f32_e32 v30, v114, v114
	v_max_f32_e32 v30, v7, v30
	v_add_f32_e32 v5, v30, v130
	v_mov_b32_e32 v147, v5
	v_max_f32_e32 v7, v5, v5
	v_max_f32_e32 v31, v115, v115
	v_max_f32_e32 v31, v7, v31
	v_add_f32_e32 v5, v31, v131
	ds_write_b128 v6, v[132:135] offset:128
	ds_write_b128 v6, v[136:139] offset:144
	ds_write_b128 v6, v[140:143] offset:160
	ds_write_b128 v6, v[144:147] offset:176
	ds_write_b128 v6, v[16:19] offset:192
	ds_write_b128 v6, v[20:23] offset:208
	ds_write_b128 v6, v[24:27] offset:224
	ds_write_b128 v6, v[28:31] offset:240

; #define LAS __attribute__((address_space(3)))
; __device__ __forceinline__ void p4_attn(const Params& p, LAS unsigned char* lds, const int dummy) {
;     ...
;             const int row = tid >> 1, pv = tid & 1; const int jk = blk * 128 - 128 + row;
;             u32x4 o1 = kr[0], o2 = kr[1];
;             if (jk >= 0) {
;                 const int pos = jk * dil + rr;
;                 float x1[8], x2[8]; unpack8(kr[0], x1); unpack8(kr[1], x2);
;                 const float4 ca = *(const float4*)(RC + pos * 16 + 8 * pv), cb = *(const float4*)(RC + pos * 16 + 8 * pv + 4);
;                 const float4 sa = *(const float4*)(RS + pos * 16 + 8 * pv), sb = *(const float4*)(RS + pos * 16 + 8 * pv + 4);
;                 const float cc[8] = {ca.x, ca.y, ca.z, ca.w, cb.x, cb.y, cb.z, cb.w}, sn[8] = {sa.x, sa.y, sa.z, sa.w, sb.x, sb.y, sb.z, sb.w};
;                 float y1[8], y2[8];
; #pragma unroll
;                 for (int e = 0; e < 8; ++e) { y1[e] = x1[e] * cc[e] - x2[e] * sn[e]; y2[e] = x2[e] * cc[e] + x1[e] * sn[e]; }
;                 o1 = pack8(y1); o2 = pack8(y2);
;             }
;             *(LAS u32x4*)(KA + row * KA_STRIDE + (8 * pv) * 2) = o1;
;             *(LAS u32x4*)(KA + row * KA_STRIDE + (16 + 8 * pv) * 2) = o2;
.LBB0_592:
	s_ashr_i32 s1, s8, 6
	s_mul_hi_i32 s4, s1, 0x55555556
	s_lshr_b32 s5, s4, 31
	s_add_i32 s4, s4, s5
	s_mul_i32 s4, s4, 3
	s_sub_i32 s9, s1, s4
	s_lshl_b32 s4, s9, 1
	s_lshr_b32 s1, 16, s4
	s_and_b32 s0, s8, 15
	s_add_i32 s1, s1, -1
	s_and_b32 s81, s1, s0
	s_lshl_b32 s11, s81, 7
	s_sub_i32 s1, 4, s4
	v_add_u32_e32 v37, s11, v144
	s_lshr_b32 s5, s0, s1
	v_cmp_lt_i32_e32 vcc, -1, v37
	s_and_saveexec_b64 s[0:1], vcc
	s_cbranch_execz .Lat_norope
	v_lshlrev_b32_e32 v37, s4, v37
	v_add_lshl_u32 v38, v37, s5, 4
	v_mov_b32_e32 v39, v36
	v_lshlrev_b64 v[38:39], 2, v[38:39]
	v_lshl_add_u64 v[72:73], v[112:113], 0, v[38:39]
	v_lshl_add_u64 v[38:39], v[114:115], 0, v[38:39]
	global_load_dwordx4 v[68:71], v[72:73], off offset:16
	s_nop 0
	global_load_dwordx4 v[72:75], v[72:73], off
	s_nop 0
	global_load_dwordx4 v[76:79], v[38:39], off offset:16
	global_load_dwordx4 v[80:83], v[38:39], off
.Lat_norope:
	s_or_b64 exec, exec, s[0:1]
	s_waitcnt vmcnt(0)
	v_mov_b64_e32 v[102:103], v[6:7]
	v_mov_b64_e32 v[98:99], v[2:3]
	v_mov_b64_e32 v[100:101], v[4:5]
	v_mov_b64_e32 v[96:97], v[0:1]
	s_and_saveexec_b64 s[0:1], vcc
	s_cbranch_execz .LBB0_594
	v_lshlrev_b32_e32 v84, 16, v0
	v_and_b32_e32 v85, 0xffff0000, v0
	v_lshlrev_b32_e32 v86, 16, v4
	v_and_b32_e32 v87, 0xffff0000, v4
	v_pk_mul_f32 v[38:39], v[80:81], v[84:85]
	v_pk_mul_f32 v[80:81], v[80:81], v[86:87]
	v_pk_fma_f32 v[38:39], v[72:73], v[86:87], v[38:39]
	v_pk_fma_f32 v[72:73], v[72:73], v[84:85], v[80:81] neg_lo:[0,0,1] neg_hi:[0,0,1]
	v_lshlrev_b32_e32 v80, 16, v1
	v_and_b32_e32 v81, 0xffff0000, v1
	v_lshlrev_b32_e32 v84, 16, v5
	v_and_b32_e32 v85, 0xffff0000, v5
	v_pk_mul_f32 v[86:87], v[82:83], v[80:81]
	v_pk_mul_f32 v[82:83], v[82:83], v[84:85]
	v_pk_fma_f32 v[86:87], v[74:75], v[84:85], v[86:87]
	v_pk_fma_f32 v[74:75], v[74:75], v[80:81], v[82:83] neg_lo:[0,0,1] neg_hi:[0,0,1]
	v_lshlrev_b32_e32 v80, 16, v2
	v_and_b32_e32 v81, 0xffff0000, v2
	v_lshlrev_b32_e32 v82, 16, v6
	v_and_b32_e32 v83, 0xffff0000, v6
	v_pk_mul_f32 v[84:85], v[76:77], v[80:81]
	v_pk_mul_f32 v[76:77], v[76:77], v[82:83]
	v_pk_fma_f32 v[84:85], v[68:69], v[82:83], v[84:85]
	v_pk_fma_f32 v[68:69], v[68:69], v[80:81], v[76:77] neg_lo:[0,0,1] neg_hi:[0,0,1]
	v_lshlrev_b32_e32 v76, 16, v3
	v_and_b32_e32 v77, 0xffff0000, v3
	v_lshlrev_b32_e32 v80, 16, v7
	v_and_b32_e32 v81, 0xffff0000, v7
	v_pk_mul_f32 v[82:83], v[78:79], v[76:77]
	v_pk_mul_f32 v[78:79], v[78:79], v[80:81]
	v_pk_fma_f32 v[82:83], v[70:71], v[80:81], v[82:83]
	v_pk_fma_f32 v[70:71], v[70:71], v[76:77], v[78:79] neg_lo:[0,0,1] neg_hi:[0,0,1]
	v_cvt_pk_bf16_f32 v96, v72, v73
	v_cvt_pk_bf16_f32 v97, v74, v75
	v_cvt_pk_bf16_f32 v98, v68, v69
	v_cvt_pk_bf16_f32 v99, v70, v71
	v_cvt_pk_bf16_f32 v100, v38, v39
	v_cvt_pk_bf16_f32 v101, v86, v87
	v_cvt_pk_bf16_f32 v102, v84, v85
	v_cvt_pk_bf16_f32 v103, v82, v83
